# baseline (speedup 1.0000x reference)
; #define LAS __attribute__((address_space(3)))
; __device__ __forceinline__ void pool_units(LAS unsigned char* lds, const bf16* Z, const float* state, const bf16* Wpt, const float* pscale, bf16* MIXIN, int bx, int G, int tid, int wid, int lane) {
;     ...
;         { const int rb = tid >> 5, cgx = tid & 31;
;           *(LAS v4u*)(Ul + rb * PL_DS + cgx * 8) = R.c0; *(LAS v4u*)(Ul + (rb + 16) * PL_DS + cgx * 8) = R.c1; *(LAS v4u*)(Ul + (rb + 32) * PL_DS + cgx * 8) = R.c2;
;           *(LAS v4u*)(Ul + (rb + 48) * PL_DS + cgx * 8) = R.c3; if (rb + 64 < 79) *(LAS v4u*)(Ul + (rb + 64) * PL_DS + cgx * 8) = R.c4; }
;         const int fr = lane & 15, fq = lane >> 4;
;         const bf16* wb = Wpt + (size_t)g * 65536 + (size_t)(32 * wid + fr) * 256 + fq * 8;
;         bf16x8 wa[8][2];
; #pragma unroll
;         for (int ks = 0; ks < 8; ++ks)
; #pragma unroll
;             for (int nt = 0; nt < 2; ++nt) wa[ks][nt] = *(const bf16x8*)(wb + nt * 16 * 256 + ks * 32);
;         f32x4 psc[2];
; #pragma unroll
;         for (int nt = 0; nt < 2; ++nt) psc[nt] = *(const f32x4*)(pscale + g * 256 + 32 * wid + 16 * nt + fq * 4);
;         __syncthreads();
;         if (u + G < NATT) pool_load(R, Z, state, (u + G) >> 2, (u + G) & 3, tid);
.Lpool_head2:
	s_waitcnt vmcnt(8)
	ds_write_b128 v108, v[4:7]
	ds_write_b128 v108, v[8:11] offset:8448
	ds_write_b128 v108, v[12:15] offset:16896
	ds_write_b128 v108, v[20:23] offset:25344
	s_and_saveexec_b64 s[38:39], s[40:41]
	ds_write_b128 v108, v[52:55] offset:33792
	s_or_b64 exec, exec, s[38:39]
	s_and_b32 s5, s4, 3
	s_lshl_b32 s88, s5, 17
	v_lshl_add_u64 v[2:3], v[110:111], 0, s[88:89]
	v_add_co_u32_e32 v16, vcc, 0x2000, v2
	s_lshl_b32 s88, s5, 10
	s_nop 0
	v_addc_co_u32_e32 v17, vcc, 0, v3, vcc
	ds_read_b128 v[48:51], v242
	ds_read_b128 v[56:59], v242 offset:1024
	ds_read_b128 v[44:47], v242 offset:2048
	ds_read_b128 v[40:43], v242 offset:3072
	ds_read_b128 v[32:35], v242 offset:4096
	ds_read_b128 v[36:39], v242 offset:5120
	ds_read_b128 v[28:31], v242 offset:6144
	v_lshl_add_u64 v[2:3], v[112:113], 0, s[88:89]
	global_load_dwordx4 v[24:27], v[2:3], off
	global_load_dwordx4 v[16:19], v[2:3], off offset:64
	s_branch .Lpool_join
